# grid-barrier polling loops without s_sleep (tight polling)
# speedup vs baseline: 1.0031x; 1.0031x over previous
; __global__ void __launch_bounds__(512, 2) mega(Params p) {
;     ...
;     if (p.ph_lo < 0) { cg::this_grid().sync(); }
.LBB0_11:
	s_nop 0
	global_load_dword v3, v2, s[6:7] offset:32 sc1
	s_waitcnt vmcnt(0)
	v_and_b32_e32 v3, 0xffff0000, v3
	v_cmp_ne_u32_e32 vcc, v3, v1
	s_or_b64 s[8:9], vcc, s[8:9]
	s_andn2_b64 exec, exec, s[8:9]
	s_cbranch_execnz .LBB0_11

; __device__ __forceinline__ unsigned xb_ld(unsigned* p)              { return __hip_atomic_load(p, __ATOMIC_RELAXED, __HIP_MEMORY_SCOPE_AGENT); }
; __device__ __forceinline__ void xcd_barrier(unsigned* bar, volatile LAS unsigned* st, int wave_s) {
;     ...
;         if (nloc == 0u) {
;             const unsigned G = gridDim.x; unsigned sum, cnt, mine;
;             for (;;) { sum = 0u; cnt = 0u; mine = 0u;
; #pragma unroll
;                 for (unsigned j = 0; j < 16; ++j) { const unsigned c = xb_ld(&bar[XB_XCNT(j)]); sum += c; cnt += (c > 0u) ? 1u : 0u; mine = (j == x) ? c : mine; }
;                 if (sum == G) break;
;                 __builtin_amdgcn_s_sleep(1); }
.LBB0_75:
	global_load_dword v15, v16, s[6:7] sc1
	s_waitcnt lgkmcnt(0)
	global_load_dword v0, v16, s[8:9] sc1
	global_load_dword v1, v16, s[10:11] sc1
	global_load_dword v2, v16, s[12:13] sc1
	global_load_dword v3, v16, s[14:15] sc1
	global_load_dword v4, v16, s[16:17] sc1
	global_load_dword v5, v16, s[26:27] sc1
	global_load_dword v6, v16, s[28:29] sc1
	global_load_dword v7, v16, s[30:31] sc1
	global_load_dword v8, v16, s[34:35] sc1
	global_load_dword v9, v16, s[36:37] sc1
	global_load_dword v10, v16, s[38:39] sc1
	global_load_dword v11, v16, s[40:41] sc1
	global_load_dword v12, v16, s[42:43] sc1
	global_load_dword v13, v16, s[44:45] sc1
	global_load_dword v14, v16, s[46:47] sc1
	s_mov_b64 s[48:49], -1
	s_waitcnt vmcnt(14)
	v_add_u32_e32 v17, v0, v15
	s_waitcnt vmcnt(13)
	v_add_u32_e32 v17, v17, v1
	s_waitcnt vmcnt(12)
	v_add_u32_e32 v17, v17, v2
	s_waitcnt vmcnt(11)
	v_add_u32_e32 v17, v17, v3
	s_waitcnt vmcnt(10)
	v_add_u32_e32 v17, v17, v4
	s_waitcnt vmcnt(9)
	v_add_u32_e32 v17, v17, v5
	s_waitcnt vmcnt(8)
	v_add_u32_e32 v17, v17, v6
	s_waitcnt vmcnt(7)
	v_add_u32_e32 v17, v17, v7
	s_waitcnt vmcnt(6)
	v_add_u32_e32 v17, v17, v8
	s_waitcnt vmcnt(5)
	v_add_u32_e32 v17, v17, v9
	s_waitcnt vmcnt(4)
	v_add_u32_e32 v17, v17, v10
	s_waitcnt vmcnt(3)
	v_add_u32_e32 v17, v17, v11
	s_waitcnt vmcnt(2)
	v_add_u32_e32 v17, v17, v12
	s_waitcnt vmcnt(1)
	v_add_u32_e32 v17, v17, v13
	s_waitcnt vmcnt(0)
	v_add_u32_e32 v17, v17, v14
	v_cmp_eq_u32_e32 vcc, s33, v17
	s_cbranch_vccnz .LBB0_74
	s_mov_b64 s[48:49], 0
	s_nop 0
	s_branch .LBB0_74

; __device__ __forceinline__ unsigned xb_ld(unsigned* p)              { return __hip_atomic_load(p, __ATOMIC_RELAXED, __HIP_MEMORY_SCOPE_AGENT); }
; __device__ __forceinline__ unsigned xb_add(unsigned* p, unsigned v) { return __hip_atomic_fetch_add(p, v, __ATOMIC_RELAXED, __HIP_MEMORY_SCOPE_AGENT); }
; __device__ __forceinline__ void xcd_barrier(unsigned* bar, volatile LAS unsigned* st, int wave_s) {
;     ...
;             const unsigned og = xb_add(&bar[XB_TOP], 1u);
;             const unsigned tg = og / nx;
;             if (og + 1u == (tg + 1u) * nx) xb_add(&bar[XB_TOPGEN], 1u);
;             else { while (xb_ld(&bar[XB_TOPGEN]) == tg) __builtin_amdgcn_s_sleep(1); }
.LBB0_83:
	s_nop 0
	global_load_dword v1, v0, s[10:11] sc1
	s_waitcnt vmcnt(0)
	v_cmp_ne_u32_e32 vcc, v1, v2
	s_or_b64 s[14:15], vcc, s[14:15]
	s_andn2_b64 exec, exec, s[14:15]
	s_cbranch_execnz .LBB0_83

; __device__ __forceinline__ unsigned xb_ld(unsigned* p)              { return __hip_atomic_load(p, __ATOMIC_RELAXED, __HIP_MEMORY_SCOPE_AGENT); }
; __device__ __forceinline__ void xcd_barrier(unsigned* bar, volatile LAS unsigned* st, int wave_s) {
;     ...
;         } else {
;             while (xb_ld(&bar[XB_XGEN(x)]) == gen) __builtin_amdgcn_s_sleep(1);
;             __builtin_amdgcn_fence(__ATOMIC_ACQUIRE, "agent");
;             asm volatile("s_waitcnt vmcnt(0)" ::: "memory");
.LBB0_91:
	s_nop 0
	global_load_dword v2, v0, s[8:9] sc1
	s_waitcnt vmcnt(0)
	v_cmp_ne_u32_e32 vcc, v2, v1
	s_or_b64 s[14:15], vcc, s[14:15]
	s_andn2_b64 exec, exec, s[14:15]
	s_cbranch_execnz .LBB0_91
